# L0 out-proj ctx tiles overlap ff1: WGs 0-15 arrive early at phase-6 barrier, release ctx tile via counter; ff1 ctx tiles on WGs 16-79 acquire it
# speedup vs baseline: 1.0031x; 1.0031x over previous
.LBB0_363:
	s_cmp_eq_u32 s12, 6
	s_cbranch_scc0 .Lq_not6
	s_mov_b32 s67, 0x8000
	s_mov_b32 s91, 16
	s_mov_b32 s88, 1
	s_mov_b32 s90, 32
	s_movk_i32 s89, 0x80
.Lq_not6:
	s_cmp_eq_u32 s12, 7
	s_cbranch_scc0 .Lq_not7
	s_mov_b32 s67, 0x8000
	s_mov_b32 s91, 64
	s_mov_b32 s88, 1
	s_mov_b32 s90, 32
	s_movk_i32 s89, 0x80

.LBB0_376:
	s_add_i32 s52, s52, 1
	s_cmp_eq_u32 s52, 5
	s_cbranch_scc0 .Lq_h1_skip
	s_cmp_eq_u32 s12, 6
	s_cbranch_scc0 .Lq_h1_skip
	s_cmp_lt_u32 s84, 16
	s_cbranch_scc0 .Lq_h1_skip
	s_waitcnt vmcnt(0) lgkmcnt(0)
	s_barrier
	s_barrier
	s_mov_b64 s[68:69], exec
	v_readlane_b32 s70, v253, 1
	v_readlane_b32 s71, v253, 2
	s_nop 1
	s_and_b64 s[70:71], s[68:69], s[70:71]
	s_mov_b64 exec, s[70:71]
	s_cbranch_execz .Lq_h1_end
	v_readlane_b32 s72, v253, 46
	v_readlane_b32 s73, v253, 47
	v_readlane_b32 s74, v253, 40
	v_readlane_b32 s75, v253, 41
	v_readlane_b32 s0, v253, 54
	v_readlane_b32 s1, v253, 55
	s_nop 4
	v_mov_b32_e32 v2, s0
	v_mov_b32_e32 v3, s1
	ds_read_b32 v4, v2
	ds_read_b32 v5, v3
	global_load_dword v6, v1, s[72:73] sc1
	s_waitcnt vmcnt(0) lgkmcnt(0)
	v_readfirstlane_b32 s43, v6
	s_nop 3
	v_writelane_b32 v255, s43, 2
	global_atomic_add v7, v1, v208, s[74:75] sc0
	s_waitcnt vmcnt(0)
	v_add_u32_e32 v7, 1, v7
	v_add_u32_e32 v8, 1, v6
	v_mul_lo_u32 v9, v8, v4
	v_cmp_eq_u32_e32 vcc, v7, v9
	s_cbranch_vccz .Lq_h1_end
	buffer_wbl2 sc1
	s_waitcnt vmcnt(0) lgkmcnt(0)
	v_readlane_b32 s74, v253, 44
	v_readlane_b32 s75, v253, 45
	s_nop 4
	global_atomic_add v7, v1, v208, s[74:75] sc0
	s_waitcnt vmcnt(0)
	v_add_u32_e32 v7, 1, v7
	v_mul_lo_u32 v9, v8, v5
	v_cmp_eq_u32_e32 vcc, v7, v9
	s_cbranch_vccz .Lq_h1_end
	global_atomic_add v1, v208, s[72:73]
	s_waitcnt vmcnt(0)
.Lq_h1_end:
	s_mov_b64 exec, s[68:69]
.Lq_h1_skip:
	v_readlane_b32 s0, v253, 7
	s_mul_i32 s0, s52, s0
	s_mul_hi_u32 s1, s52, s28
	s_add_i32 s1, s1, s0
	s_mul_i32 s0, s52, s28
	s_add_u32 s72, s0, s84
	s_addc_u32 s73, s1, s53
	s_sub_i32 s43, s72, s50
	s_cmp_eq_u32 s12, 7
	s_cselect_b32 s0, 16, 0
	s_sub_i32 s43, s43, s0
	v_mov_b64_e32 v[2:3], s[50:51]
	s_cmp_lt_u32 s43, s91
	v_cmp_lt_i64_e64 s[0:1], s[72:73], v[2:3]
	s_cselect_b64 s[48:49], -1, 0
	s_or_b64 s[48:49], s[0:1], s[48:49]
	s_xor_b64 s[68:69], s[48:49], -1
	s_cmp_eq_u32 s12, 7
	s_cbranch_scc0 .Lq_h2_skip
	s_and_b64 vcc, exec, s[0:1]
	s_cbranch_vccnz .Lq_h2_skip
	s_and_b64 vcc, exec, s[48:49]
	s_cbranch_vccz .Lq_h2_skip
	v_readlane_b32 s74, v253, 46
	v_readlane_b32 s75, v253, 47
	s_mov_b32 s3, 0
	s_nop 4
.Lq_h2_spin:
	global_load_dword v0, v1, s[74:75] offset:768 sc1
	s_waitcnt vmcnt(0)
	v_readfirstlane_b32 s7, v0
	s_cmp_ge_u32 s7, 16
	s_cbranch_scc1 .Lq_h2_done
	s_add_i32 s3, s3, 1
	s_cmp_lt_u32 s3, 0x4000
	s_cbranch_scc0 .Lq_h2_done
	s_sleep 1
	s_branch .Lq_h2_spin
.Lq_h2_done:
	buffer_inv sc1
	s_waitcnt vmcnt(0)
.Lq_h2_skip:
	s_and_b64 vcc, exec, s[68:69]
	s_cbranch_vccnz .LBB0_382
	s_and_b64 s[70:71], s[0:1], exec
	s_cselect_b32 s7, s72, 0
	s_ashr_i32 s3, s7, 31
	s_lshr_b32 s3, s3, 29
	s_add_i32 s3, s7, s3
	s_and_b32 s57, s3, -8
	s_sub_i32 s7, s7, s57
	s_cmp_ge_i32 s7, s56
	s_mov_b64 s[70:71], -1
	s_cbranch_scc0 .LBB0_379
	s_sub_i32 s57, s7, s56
	v_readlane_b32 s70, v252, 11
	s_mul_i32 s57, s57, s70
	v_readlane_b32 s70, v252, 7
	s_mul_i32 s70, s70, s56
	s_add_i32 s57, s57, s70
	s_mov_b64 s[70:71], 0

.LBB0_617:
	s_cmp_eq_u32 s12, 7
	s_cbranch_scc0 .Lq_bar_normal
	v_readlane_b32 s2, v253, 0
	s_nop 1
	s_cmp_lt_u32 s2, 16
	s_cbranch_scc0 .Lq_bar_normal
	s_waitcnt vmcnt(0) lgkmcnt(0)
	s_barrier
	s_mov_b64 s[0:1], exec
	v_readlane_b32 s2, v253, 1
	v_readlane_b32 s3, v253, 2
	s_nop 1
	s_and_b64 s[2:3], s[0:1], s[2:3]
	s_mov_b64 exec, s[2:3]
	s_cbranch_execz .LBB0_185
	buffer_wbl2 sc1
	s_waitcnt vmcnt(0) lgkmcnt(0)
	v_readlane_b32 s4, v253, 46
	v_readlane_b32 s5, v253, 47
	v_readlane_b32 s6, v255, 2
	s_mov_b32 s16, 0
	s_nop 4
	global_atomic_add v1, v208, s[4:5] offset:768
.Lq_wa_spin:
	global_load_dword v2, v1, s[4:5] sc1
	s_waitcnt vmcnt(0)
	v_readfirstlane_b32 s7, v2
	s_cmp_lg_u32 s7, s6
	s_cbranch_scc1 .Lq_wa_done
	s_add_i32 s16, s16, 1
	s_cmp_lt_u32 s16, 0x4000
	s_cbranch_scc0 .Lq_wa_done
	s_sleep 1
	s_branch .Lq_wa_spin
.Lq_wa_done:
	s_waitcnt vmcnt(0)
	buffer_inv sc1
	s_waitcnt vmcnt(0)
	s_branch .LBB0_185
